# HGRN pass 3: gate-row load issued with the parked forward half in the backward output stage; carried-in state loop loads batched (40 loads, one wait per segment step)
# speedup vs baseline: 1.0250x; 1.0094x over previous
; template <int PASS>
; DEV void hgrn_task(unsigned char* lds, int task, int l, const bf16_t* BZ, float* E, float* Dd, float* OF, bf16_t* YB, const float* b_lb, const float* gout) {
;     ...
;             for (int q = 0; q < 15; ++q) { const int sp = dir ? 15 - q : q; if (dir ? (sp <= seg) : (sp >= seg)) break;
;                 const int tk = ((task & ~15) + sp) * 2 + dir; const float* dp = Dd + tk * 128; const float* ep = E + (size_t)tk * 8192 + 16 * nt + fr;
; #pragma unroll
;                 for (int mt = 0; mt < 8; ++mt)
; #pragma unroll
;                     for (int i = 0; i < 4; ++i) { const int k = 16 * mt + 4 * fq + i; st[mt][i] = dp[k] * st[mt][i] + ep[k * 64]; } }
.LBB0_560:
	s_and_b64 s[4:5], s[28:29], exec
	s_cselect_b32 s4, s35, s49
	s_add_i32 s4, s4, s74
	s_lshl_b32 s4, s4, 1
	s_or_b32 s4, s4, s34
	s_ashr_i32 s5, s4, 31
	s_lshl_b32 s6, s4, 7
	s_lshl_b64 s[4:5], s[4:5], 15
	v_lshl_add_u64 v[34:35], v[62:63], 0, s[4:5]
	v_mov_b32_e32 v69, v128
	s_ashr_i32 s7, s6, 31
	v_lshl_add_u64 v[38:39], v[34:35], 0, v[68:69]
	v_lshl_add_u64 v[36:37], s[6:7], 2, v[66:67]
	v_mov_b64_e32 v[142:143], v[38:39]
	flat_load_dword v110, v[142:143]
	flat_load_dword v111, v[142:143] offset:256
	flat_load_dword v112, v[142:143] offset:512
	flat_load_dword v113, v[142:143] offset:768
	flat_load_dwordx4 v[130:133], v[36:37]
	v_add_co_u32_e32 v142, vcc, 0x1000, v142
	s_nop 1
	v_addc_co_u32_e32 v143, vcc, 0, v143, vcc
	flat_load_dword v114, v[142:143]
	flat_load_dword v115, v[142:143] offset:256
	flat_load_dword v116, v[142:143] offset:512
	flat_load_dword v117, v[142:143] offset:768
	flat_load_dwordx4 v[134:137], v[36:37] offset:64
	v_add_co_u32_e32 v142, vcc, 0x1000, v142
	s_nop 1
	v_addc_co_u32_e32 v143, vcc, 0, v143, vcc
	flat_load_dword v118, v[142:143]
	flat_load_dword v119, v[142:143] offset:256
	flat_load_dword v120, v[142:143] offset:512
	flat_load_dword v121, v[142:143] offset:768
	flat_load_dwordx4 v[138:141], v[36:37] offset:128
	v_add_co_u32_e32 v142, vcc, 0x1000, v142
	s_nop 1
	v_addc_co_u32_e32 v143, vcc, 0, v143, vcc
	flat_load_dword v122, v[142:143]
	flat_load_dword v123, v[142:143] offset:256
	flat_load_dword v124, v[142:143] offset:512
	flat_load_dword v125, v[142:143] offset:768
	flat_load_dwordx4 v[194:197], v[36:37] offset:192
	v_add_co_u32_e32 v142, vcc, 0x1000, v142
	s_nop 1
	v_addc_co_u32_e32 v143, vcc, 0, v143, vcc
	flat_load_dword v200, v[142:143]
	flat_load_dword v201, v[142:143] offset:256
	flat_load_dword v202, v[142:143] offset:512
	flat_load_dword v203, v[142:143] offset:768
	flat_load_dwordx4 v[50:53], v[36:37] offset:256
	v_add_co_u32_e32 v142, vcc, 0x1000, v142
	s_nop 1
	v_addc_co_u32_e32 v143, vcc, 0, v143, vcc
	flat_load_dword v204, v[142:143]
	flat_load_dword v205, v[142:143] offset:256
	flat_load_dword v244, v[142:143] offset:512
	flat_load_dword v245, v[142:143] offset:768
	flat_load_dwordx4 v[106:109], v[36:37] offset:320
	v_add_co_u32_e32 v142, vcc, 0x1000, v142
	s_nop 1
	v_addc_co_u32_e32 v143, vcc, 0, v143, vcc
	flat_load_dword v246, v[142:143]
	flat_load_dword v247, v[142:143] offset:256
	flat_load_dword v248, v[142:143] offset:512
	flat_load_dword v249, v[142:143] offset:768
	flat_load_dwordx4 v[40:43], v[36:37] offset:384
	v_add_co_u32_e32 v142, vcc, 0x1000, v142
	s_nop 1
	v_addc_co_u32_e32 v143, vcc, 0, v143, vcc
	flat_load_dword v250, v[142:143]
	flat_load_dword v251, v[142:143] offset:256
	flat_load_dword v252, v[142:143] offset:512
	flat_load_dword v253, v[142:143] offset:768
	flat_load_dwordx4 v[44:47], v[36:37] offset:448
	s_add_i32 s35, s35, 1
	s_add_i32 s49, s49, -1
	s_cmp_eq_u32 s35, 15
	s_cselect_b64 s[4:5], -1, 0
	s_waitcnt vmcnt(0) lgkmcnt(0)
	v_pk_fma_f32 v[2:3], v[2:3], v[130:131], v[110:111]
	v_pk_fma_f32 v[4:5], v[4:5], v[132:133], v[112:113]
	v_pk_fma_f32 v[6:7], v[6:7], v[134:135], v[114:115]
	v_pk_fma_f32 v[8:9], v[8:9], v[136:137], v[116:117]
	v_pk_fma_f32 v[10:11], v[10:11], v[138:139], v[118:119]
	v_pk_fma_f32 v[12:13], v[12:13], v[140:141], v[120:121]
	v_pk_fma_f32 v[14:15], v[14:15], v[194:195], v[122:123]
	v_pk_fma_f32 v[16:17], v[16:17], v[196:197], v[124:125]
	v_pk_fma_f32 v[18:19], v[18:19], v[50:51], v[200:201]
	v_pk_fma_f32 v[20:21], v[20:21], v[52:53], v[202:203]
	v_pk_fma_f32 v[22:23], v[22:23], v[106:107], v[204:205]
	v_pk_fma_f32 v[24:25], v[24:25], v[108:109], v[244:245]
	v_pk_fma_f32 v[26:27], v[26:27], v[40:41], v[246:247]
	v_pk_fma_f32 v[28:29], v[28:29], v[42:43], v[248:249]
	v_pk_fma_f32 v[30:31], v[30:31], v[44:45], v[250:251]
	v_pk_fma_f32 v[32:33], v[32:33], v[46:47], v[252:253]
	s_andn2_b64 vcc, exec, s[4:5]
	s_cbranch_vccz .LBB0_568

; DEV unsigned pk2(float lo, float hi) { return pg8::cvt_pk_bf16(lo, hi); }
; DEV float sigmoidf_(float z) { return __builtin_amdgcn_rcpf(1.f + __expf(-z)); }
; template <int PASS>
; DEV void hgrn_task(unsigned char* lds, int task, int l, const bf16_t* BZ, float* E, float* Dd, float* OF, bf16_t* YB, const float* b_lb, const float* gout) {
;     ...
;                 f32x4 o0 = *(const f32x4*)(OUT + ps * 64 + n8), o1 = *(const f32x4*)(OUT + ps * 64 + n8 + 4);
;                 float* ofp = OF + (size_t)row * 512 + h * 64 + n8;
;                 if (dir == 0) { *(f32x4*)ofp = o0; *(f32x4*)(ofp + 4) = o1; }
;                 else { o0 += *(const f32x4*)ofp; o1 += *(const f32x4*)(ofp + 4);
;                     float sq = ((o0[0] * o0[0] + o0[1] * o0[1]) + (o0[2] * o0[2] + o0[3] * o0[3])) + ((o1[0] * o1[0] + o1[1] * o1[1]) + (o1[2] * o1[2] + o1[3] * o1[3]));
;                     sq += __shfl_xor(sq, 1); sq += __shfl_xor(sq, 2); sq += __shfl_xor(sq, 4);
;                     const float rn = rsqrtf(sq * (1.f / 64.f) + EPS); const u32x4 gw = *(const u32x4*)(BZ + (size_t)row * 4096 + 3584 + h * 64 + n8);
;                     const f32x4 g0v = {__uint_as_float(gw.x << 16), __uint_as_float(gw.x & 0xffff0000u), __uint_as_float(gw.y << 16), __uint_as_float(gw.y & 0xffff0000u)};
;                     const f32x4 g1v = {__uint_as_float(gw.z << 16), __uint_as_float(gw.z & 0xffff0000u), __uint_as_float(gw.w << 16), __uint_as_float(gw.w & 0xffff0000u)};
;                     const f32x4 go0 = *(const f32x4*)(gout + l * 64 + n8), go1 = *(const f32x4*)(gout + l * 64 + n8 + 4); f32x4 y0, y1;
; #pragma unroll
;                     for (int j = 0; j < 4; ++j) { y0[j] = o0[j] * rn * go0[j] * (g0v[j] * sigmoidf_(g0v[j])); y1[j] = o1[j] * rn * go1[j] * (g1v[j] * sigmoidf_(g1v[j])); }
;                     u32x4 yw; yw.x = pk2(y0[0], y0[1]); yw.y = pk2(y0[2], y0[3]); yw.z = pk2(y1[0], y1[1]); yw.w = pk2(y1[2], y1[3]);
;                     *(u32x4*)(YB + (size_t)row * 512 + h * 64 + n8) = yw; }
.LBB0_577:
	flat_load_dwordx4 v[48:51], v[114:115]
	v_lshlrev_b64 v[116:117], 9, v[46:47]
	v_lshlrev_b64 v[46:47], 13, v[46:47]
	v_lshl_add_u64 v[46:47], s[20:21], 0, v[46:47]
	v_lshl_add_u64 v[46:47], v[46:47], 0, s[66:67]
	v_mov_b32_e32 v103, v128
	v_lshl_add_u64 v[46:47], v[46:47], 0, v[102:103]
	v_add_co_u32_e32 v46, vcc, s62, v46
	s_nop 1
	v_addc_co_u32_e32 v47, vcc, 0, v47, vcc
	flat_load_dwordx4 v[202:205], v[46:47] offset:3072
	s_waitcnt vmcnt(0) lgkmcnt(0)
	v_pk_add_f32 v[124:125], v[40:41], v[50:51]
	v_pk_add_f32 v[132:133], v[38:39], v[48:49]
	flat_load_dwordx4 v[48:51], v[114:115] offset:16
	v_mov_b32_e32 v52, v125
	s_waitcnt vmcnt(0) lgkmcnt(0)
	v_pk_add_f32 v[134:135], v[42:43], v[48:49]
	v_pk_add_f32 v[120:121], v[44:45], v[50:51]
	v_mov_b32_e32 v50, v133
	v_mov_b32_e32 v51, v135
	v_mov_b32_e32 v48, v132
	v_mov_b32_e32 v49, v134
	v_pk_mul_f32 v[50:51], v[50:51], v[50:51]
	v_mov_b32_e32 v53, v121
	v_pk_fma_f32 v[48:49], v[48:49], v[48:49], v[50:51]
	v_mov_b32_e32 v50, v124
	v_mov_b32_e32 v51, v120
	v_pk_mul_f32 v[52:53], v[52:53], v[52:53]
	s_nop 0
	v_pk_fma_f32 v[50:51], v[50:51], v[50:51], v[52:53]
	s_nop 0
	v_pk_add_f32 v[48:49], v[48:49], v[50:51]
	v_and_b32_e32 v50, 64, v227
	v_add_f32_e32 v48, v48, v49
	v_xor_b32_e32 v49, 1, v227
	v_add_u32_e32 v50, 64, v50
	v_cmp_lt_i32_e32 vcc, v49, v50
	s_nop 1
	v_cndmask_b32_e32 v49, v227, v49, vcc
	v_lshlrev_b32_e32 v49, 2, v49
	ds_bpermute_b32 v49, v49, v48
	s_waitcnt lgkmcnt(0)
	v_add_f32_e32 v48, v48, v49
	v_xor_b32_e32 v49, 2, v227
	v_cmp_lt_i32_e32 vcc, v49, v50
	s_nop 1
	v_cndmask_b32_e32 v49, v227, v49, vcc
	v_lshlrev_b32_e32 v49, 2, v49
	ds_bpermute_b32 v49, v49, v48
	s_waitcnt lgkmcnt(0)
	v_add_f32_e32 v48, v48, v49
	v_xor_b32_e32 v49, 4, v227
	v_cmp_lt_i32_e32 vcc, v49, v50
	s_nop 1
	v_cndmask_b32_e32 v49, v227, v49, vcc
	v_lshlrev_b32_e32 v49, 2, v49
	ds_bpermute_b32 v49, v49, v48
	s_waitcnt lgkmcnt(0)
	v_add_f32_e32 v48, v48, v49
	v_fmamk_f32 v48, v48, 0x3c800000, v226
	v_cmp_gt_f32_e32 vcc, s57, v48
	v_mul_f32_e32 v49, 0x4b800000, v48
	s_nop 0
	v_cndmask_b32_e32 v48, v48, v49, vcc
	v_rsq_f32_e32 v48, v48
	s_nop 0
	v_mul_f32_e32 v49, 0x45800000, v48
	v_cndmask_b32_e32 v104, v48, v49, vcc
	v_mul_f32_e32 v143, v132, v104
	s_nop 0
	v_mul_f32_e32 v137, v135, v104
	v_mul_f32_e32 v139, v133, v104
	v_mul_f32_e32 v131, v124, v104
	v_mul_f32_e32 v141, v134, v104
	v_mul_f32_e32 v127, v120, v104
	v_mul_f32_e32 v123, v125, v104
	v_mul_f32_e32 v119, v121, v104
	s_waitcnt vmcnt(0) lgkmcnt(0)
	v_lshlrev_b32_e32 v142, 16, v202
	v_and_b32_e32 v138, 0xffff0000, v202
	v_lshlrev_b32_e32 v130, 16, v203
	v_and_b32_e32 v122, 0xffff0000, v203
	v_lshlrev_b32_e32 v140, 16, v204
	v_and_b32_e32 v136, 0xffff0000, v204
	v_lshlrev_b32_e32 v126, 16, v205
	v_and_b32_e32 v118, 0xffff0000, v205
	flat_load_dwordx4 v[50:53], v[64:65]
	flat_load_dwordx4 v[46:49], v[64:65] offset:16
	v_mul_f32_e32 v103, 0xbfb8aa3b, v142
	v_exp_f32_e32 v103, v103
	s_waitcnt vmcnt(0) lgkmcnt(0)
	v_mov_b32_e32 v201, v50
	v_add_f32_e32 v103, 1.0, v103
	v_rcp_f32_e32 v200, v103
	v_mul_f32_e32 v50, 0xbfb8aa3b, v140
	v_exp_f32_e32 v50, v50
	v_mov_b32_e32 v133, v52
	v_pk_mul_f32 v[142:143], v[200:201], v[142:143]
	v_add_f32_e32 v50, 1.0, v50
	v_mul_f32_e32 v103, v142, v143
	v_mov_b32_e32 v143, v46
	v_mul_f32_e32 v46, 0xbfb8aa3b, v138
	v_exp_f32_e32 v46, v46
	v_rcp_f32_e32 v142, v50
	v_add_f32_e32 v46, 1.0, v46
	v_rcp_f32_e32 v50, v46
	v_mul_f32_e32 v46, 0xbfb8aa3b, v136
	v_exp_f32_e32 v46, v46
	v_pk_mul_f32 v[140:141], v[142:143], v[140:141]
	v_pk_mul_f32 v[50:51], v[50:51], v[138:139]
	v_mul_f32_e32 v108, v140, v141
	v_add_f32_e32 v46, 1.0, v46
	v_rcp_f32_e32 v46, v46
	v_mul_f32_e32 v50, v50, v51
	v_mul_f32_e32 v51, 0xbfb8aa3b, v126
	v_exp_f32_e32 v51, v51
	v_pk_mul_f32 v[46:47], v[46:47], v[136:137]
	v_add_f32_e32 v51, 1.0, v51
	v_mul_f32_e32 v46, v46, v47
	v_mul_f32_e32 v47, 0xbfb8aa3b, v130
	v_exp_f32_e32 v47, v47
	s_nop 0
	v_add_f32_e32 v47, 1.0, v47
	v_rcp_f32_e32 v132, v47
	s_nop 0
	v_pk_mul_f32 v[130:131], v[132:133], v[130:131]
	s_nop 0
	v_mul_f32_e32 v47, v130, v131
	v_mov_b32_e32 v131, v48
	v_mul_f32_e32 v48, 0xbfb8aa3b, v122
	v_exp_f32_e32 v48, v48
	v_rcp_f32_e32 v130, v51
	v_add_f32_e32 v48, 1.0, v48
	v_rcp_f32_e32 v52, v48
	v_mul_f32_e32 v48, 0xbfb8aa3b, v118
	v_exp_f32_e32 v48, v48
	v_pk_mul_f32 v[126:127], v[130:131], v[126:127]
	v_pk_mul_f32 v[52:53], v[52:53], v[122:123]
	v_mul_f32_e32 v51, v126, v127
	v_add_f32_e32 v48, 1.0, v48
	v_rcp_f32_e32 v48, v48
	v_mul_f32_e32 v52, v52, v53
	v_pk_mul_f32 v[48:49], v[48:49], v[118:119]
	s_nop 0
	v_mul_f32_e32 v53, v48, v49
	v_cvt_pk_bf16_f32 v48, v103, v50
	v_cvt_pk_bf16_f32 v49, v47, v52
	v_cvt_pk_bf16_f32 v50, v108, v46
	v_lshl_add_u64 v[46:47], v[116:117], 1, v[60:61]
	v_cvt_pk_bf16_f32 v51, v51, v53
	flat_store_dwordx4 v[46:47], v[48:51]
	s_cbranch_execnz .LBB0_569
